# attention phase: one static s_setprio 1 for waves 4-7 (on top of the paced version)
# baseline (speedup 1.0000x reference)
.LBB0_705:
	s_cmp_ge_u32 s62, 4
	s_cbranch_scc0 .Lprio_att
	s_setprio 1

.LBB0_742:
	s_setprio 0
	v_mov_b32_e32 v2, v234
	s_barrier
	s_lshl_b32 s5, s19, 3
	v_writelane_b32 v253, s8, 8
	s_add_i32 s10, s5, s62
	v_readlane_b32 s0, v253, 61
	v_writelane_b32 v253, s19, 7
	s_cmpk_gt_i32 s10, 0xfff
	v_mov_b32_e32 v0, s0
	v_readlane_b32 s0, v254, 5
	ds_read_b64 v[8:9], v0
	s_waitcnt lgkmcnt(0)
	v_readfirstlane_b32 s2, v8
	v_mov_b32_e32 v0, s0
	ds_read_b128 v[4:7], v0
	v_readfirstlane_b32 s3, v9
	s_waitcnt lgkmcnt(0)
	v_readfirstlane_b32 s1, v4
	v_readfirstlane_b32 s4, v5
	v_readfirstlane_b32 s0, v6
	v_readfirstlane_b32 s5, v7
	s_cbranch_scc1 .LBB0_796
	v_readlane_b32 s6, v253, 8
	v_readlane_b32 s12, v254, 60
	s_lshl_b32 s11, s6, 3
	s_mul_i32 s7, s12, 0x9000
	s_mul_hi_u32 s6, s12, 0x9000
	s_add_u32 s1, s1, s7
	s_addc_u32 s8, s4, s6
	s_lshl_b32 s4, s62, 14
	s_add_i32 s9, s4, 0
	s_mul_i32 s6, s12, 0x3000
	s_mul_hi_u32 s4, s12, 0x3000
	s_add_u32 s0, s0, s6
	s_addc_u32 s7, s5, s4
	s_add_u32 s4, s0, 0x1000
	v_lshlrev_b32_e32 v0, 2, v2
	s_addc_u32 s5, s7, 0
	v_lshlrev_b32_e32 v3, 3, v2
	v_and_b32_e32 v136, 60, v0
	s_add_u32 s6, s0, 0x2000
	v_mov_b32_e32 v0, s9
	v_and_b32_e32 v3, 56, v3
	s_movk_i32 s0, 0x88
	v_readlane_b32 s13, v254, 61
	v_mad_u32_u24 v6, v3, s0, v0
	v_lshlrev_b32_e32 v0, 1, v3
	s_addc_u32 s7, s7, 0
	v_lshl_add_u64 v[4:5], s[2:3], 0, v[0:1]
	s_mov_b64 s[12:13], 0x70800000
	v_lshl_add_u64 v[36:37], v[4:5], 0, s[12:13]
	s_add_u32 s12, s1, 0x1000
	s_addc_u32 s13, s8, 0
	s_add_u32 s20, s1, 0x2000
	s_addc_u32 s21, s8, 0
	v_add_u32_e32 v0, 64, v2
	s_add_u32 s34, s1, 0x4000
	v_ashrrev_i32_e32 v139, 3, v0
	v_add_u32_e32 v0, 0x80, v2
	s_addc_u32 s35, s8, 0
	v_ashrrev_i32_e32 v141, 3, v0
	v_add_u32_e32 v0, 0xc0, v2
	s_add_u32 s36, s1, 0x5000
	v_ashrrev_i32_e32 v143, 3, v0
	v_add_u32_e32 v0, 0x100, v2
	s_addc_u32 s37, s8, 0
	v_ashrrev_i32_e32 v145, 3, v0
	v_add_u32_e32 v0, 0x140, v2
	s_add_u32 s38, s1, 0x7000
	v_ashrrev_i32_e32 v147, 3, v0
	v_add_u32_e32 v0, 0x180, v2
	s_addc_u32 s39, s8, 0
	v_ashrrev_i32_e32 v149, 3, v0
	v_add_u32_e32 v0, 0x1c0, v2
	v_ashrrev_i32_e32 v137, 3, v2
	s_add_u32 s40, s1, 0x8000
	v_ashrrev_i32_e32 v151, 3, v0
	v_ashrrev_i32_e32 v35, 4, v2
	v_lshl_add_u32 v34, v136, 1, s9
	v_lshl_add_u32 v138, v137, 1, v6
	s_addc_u32 s41, s8, 0
	v_lshl_add_u32 v140, v139, 1, v6
	v_lshl_add_u32 v142, v141, 1, v6
	v_lshl_add_u32 v144, v143, 1, v6
	v_lshl_add_u32 v146, v145, 1, v6
	v_lshl_add_u32 v148, v147, 1, v6
	v_lshl_add_u32 v150, v149, 1, v6
	v_lshl_add_u32 v152, v151, 1, v6
	s_branch .LBB0_745
